# LayerNorm and pooling phase stores marked sc1 (device-scope write-through): L2 is clean at the release fence before the grid barrier
# speedup vs baseline: 1.0088x; 1.0088x over previous
; DI float bflo(unsigned u) { return __uint_as_float(u << 16); }
; DI float bfhi(unsigned u) { return __uint_as_float(u & 0xffff0000u); }
; template <int NR>
; DI void ln_rows(const Params& P, const LnSpec& sp, int row, int stride, int lane) {
;     ...
;     for (int k = 0; k < NR; ++k) {
;         const int r = row + k * stride;
;         const float* xp = r < RL ? sp.res_lat + (size_t)r * 1024 : sp.res_ctx + (size_t)(r - RL) * 1024;
;         const bf16_t* yp = sp.Y + (size_t)r * 1024;
; #pragma unroll
;         for (int i = 0; i < 4; ++i) {
;             const f32x4 x = __builtin_nontemporal_load((const f32x4*)(xp + (i * 64 + lane) * 4));
;             const u32x2 y = __builtin_nontemporal_load((const u32x2*)(yp + (i * 64 + lane) * 4));
;             v[k][i][0] = ALPHA * x[0] + bflo(y.x); v[k][i][1] = ALPHA * x[1] + bfhi(y.x);
;             v[k][i][2] = ALPHA * x[2] + bflo(y.y); v[k][i][3] = ALPHA * x[3] + bfhi(y.y);
;         }
;     }
; #pragma unroll
;     for (int k = 0; k < NR; ++k) {
;         s[k] = 0.f;
; #pragma unroll
;         for (int i = 0; i < 4; ++i) s[k] += (v[k][i][0] + v[k][i][1]) + (v[k][i][2] + v[k][i][3]);
.Lmy_ln1_row0:
	s_cmp_eq_u32 s18, 1
	s_cselect_b32 s3, 0, 0x4f83200
	s_add_u32 s3, s3, s2
	v_add_u32_e32 v218, s3, v170
	s_add_u32 s3, s3, 0x1000
	v_add_u32_e32 v219, s3, v170
	s_add_u32 s3, s3, 0x1000
	v_add_u32_e32 v220, s3, v170
	s_add_u32 s3, s3, 0x1000
	v_add_u32_e32 v221, s3, v170
	s_lshr_b32 s3, s2, 1
	s_add_u32 s3, s3, 0xd383200
	v_add_u32_e32 v222, s3, v171
	s_add_u32 s3, s3, 0x1000
	v_add_u32_e32 v223, s3, v171
	v_lshlrev_b32_e32 v224, 16, v64
	v_and_b32_e32 v225, 0xffff0000, v64
	v_fmamk_f32 v0, v0, 0x3fb504f3, v224
	v_fmamk_f32 v1, v1, 0x3fb504f3, v225
	v_lshlrev_b32_e32 v224, 16, v65
	v_and_b32_e32 v225, 0xffff0000, v65
	v_fmamk_f32 v2, v2, 0x3fb504f3, v224
	v_fmamk_f32 v3, v3, 0x3fb504f3, v225
	v_add_f32_e32 v226, v0, v1
	v_add_f32_e32 v227, v2, v3
	v_add_f32_e32 v226, v226, v227
	v_mov_b32_e32 v166, v226
	v_lshlrev_b32_e32 v224, 16, v66
	v_and_b32_e32 v225, 0xffff0000, v66
	v_fmamk_f32 v4, v4, 0x3fb504f3, v224
	v_fmamk_f32 v5, v5, 0x3fb504f3, v225
	v_lshlrev_b32_e32 v224, 16, v67
	v_and_b32_e32 v225, 0xffff0000, v67
	v_fmamk_f32 v6, v6, 0x3fb504f3, v224
	v_fmamk_f32 v7, v7, 0x3fb504f3, v225
	v_add_f32_e32 v226, v4, v5
	v_add_f32_e32 v227, v6, v7
	v_add_f32_e32 v226, v226, v227
	v_add_f32_e32 v166, v166, v226
	v_lshlrev_b32_e32 v224, 16, v68
	v_and_b32_e32 v225, 0xffff0000, v68
	v_fmamk_f32 v8, v8, 0x3fb504f3, v224
	v_fmamk_f32 v9, v9, 0x3fb504f3, v225
	v_lshlrev_b32_e32 v224, 16, v69
	v_and_b32_e32 v225, 0xffff0000, v69
	v_fmamk_f32 v10, v10, 0x3fb504f3, v224
	v_fmamk_f32 v11, v11, 0x3fb504f3, v225
	v_add_f32_e32 v226, v8, v9
	v_add_f32_e32 v227, v10, v11
	v_add_f32_e32 v226, v226, v227
	v_add_f32_e32 v166, v166, v226
	v_lshlrev_b32_e32 v224, 16, v70
	v_and_b32_e32 v225, 0xffff0000, v70
	v_fmamk_f32 v12, v12, 0x3fb504f3, v224
	v_fmamk_f32 v13, v13, 0x3fb504f3, v225
	v_lshlrev_b32_e32 v224, 16, v71
	v_and_b32_e32 v225, 0xffff0000, v71
	v_fmamk_f32 v14, v14, 0x3fb504f3, v224
	v_fmamk_f32 v15, v15, 0x3fb504f3, v225
	v_add_f32_e32 v226, v12, v13
	v_add_f32_e32 v227, v14, v15
	v_add_f32_e32 v226, v226, v227
	v_add_f32_e32 v166, v166, v226
	s_waitcnt vmcnt(16)
	v_lshlrev_b32_e32 v224, 16, v72
	v_and_b32_e32 v225, 0xffff0000, v72
	v_fmamk_f32 v16, v16, 0x3fb504f3, v224
	v_fmamk_f32 v17, v17, 0x3fb504f3, v225
	v_lshlrev_b32_e32 v224, 16, v73
	v_and_b32_e32 v225, 0xffff0000, v73
	v_fmamk_f32 v18, v18, 0x3fb504f3, v224
	v_fmamk_f32 v19, v19, 0x3fb504f3, v225
	v_add_f32_e32 v226, v16, v17
	v_add_f32_e32 v227, v18, v19
	v_add_f32_e32 v226, v226, v227
	v_mov_b32_e32 v167, v226
	v_lshlrev_b32_e32 v224, 16, v74
	v_and_b32_e32 v225, 0xffff0000, v74
	v_fmamk_f32 v20, v20, 0x3fb504f3, v224
	v_fmamk_f32 v21, v21, 0x3fb504f3, v225
	v_lshlrev_b32_e32 v224, 16, v75
	v_and_b32_e32 v225, 0xffff0000, v75
	v_fmamk_f32 v22, v22, 0x3fb504f3, v224
	v_fmamk_f32 v23, v23, 0x3fb504f3, v225
	v_add_f32_e32 v226, v20, v21
	v_add_f32_e32 v227, v22, v23
	v_add_f32_e32 v226, v226, v227
	v_add_f32_e32 v167, v167, v226
	v_lshlrev_b32_e32 v224, 16, v76
	v_and_b32_e32 v225, 0xffff0000, v76
	v_fmamk_f32 v24, v24, 0x3fb504f3, v224
	v_fmamk_f32 v25, v25, 0x3fb504f3, v225
	v_lshlrev_b32_e32 v224, 16, v77
	v_and_b32_e32 v225, 0xffff0000, v77
	v_fmamk_f32 v26, v26, 0x3fb504f3, v224
	v_fmamk_f32 v27, v27, 0x3fb504f3, v225
	v_add_f32_e32 v226, v24, v25
	v_add_f32_e32 v227, v26, v27
	v_add_f32_e32 v226, v226, v227
	v_add_f32_e32 v167, v167, v226
	v_lshlrev_b32_e32 v224, 16, v78
	v_and_b32_e32 v225, 0xffff0000, v78
	v_fmamk_f32 v28, v28, 0x3fb504f3, v224
	v_fmamk_f32 v29, v29, 0x3fb504f3, v225
	v_lshlrev_b32_e32 v224, 16, v79
	v_and_b32_e32 v225, 0xffff0000, v79
	v_fmamk_f32 v30, v30, 0x3fb504f3, v224
	v_fmamk_f32 v31, v31, 0x3fb504f3, v225
	v_add_f32_e32 v226, v28, v29
	v_add_f32_e32 v227, v30, v31
	v_add_f32_e32 v226, v226, v227
	v_add_f32_e32 v167, v167, v226
	s_waitcnt vmcnt(8)
	v_lshlrev_b32_e32 v224, 16, v80
	v_and_b32_e32 v225, 0xffff0000, v80
	v_fmamk_f32 v32, v32, 0x3fb504f3, v224
	v_fmamk_f32 v33, v33, 0x3fb504f3, v225
	v_lshlrev_b32_e32 v224, 16, v81
	v_and_b32_e32 v225, 0xffff0000, v81
	v_fmamk_f32 v34, v34, 0x3fb504f3, v224
	v_fmamk_f32 v35, v35, 0x3fb504f3, v225
	v_add_f32_e32 v226, v32, v33
	v_add_f32_e32 v227, v34, v35
	v_add_f32_e32 v226, v226, v227
	v_mov_b32_e32 v168, v226
	v_lshlrev_b32_e32 v224, 16, v82
	v_and_b32_e32 v225, 0xffff0000, v82
	v_fmamk_f32 v36, v36, 0x3fb504f3, v224
	v_fmamk_f32 v37, v37, 0x3fb504f3, v225
	v_lshlrev_b32_e32 v224, 16, v83
	v_and_b32_e32 v225, 0xffff0000, v83
	v_fmamk_f32 v38, v38, 0x3fb504f3, v224
	v_fmamk_f32 v39, v39, 0x3fb504f3, v225
	v_add_f32_e32 v226, v36, v37
	v_add_f32_e32 v227, v38, v39
	v_add_f32_e32 v226, v226, v227
	v_add_f32_e32 v168, v168, v226
	v_lshlrev_b32_e32 v224, 16, v84
	v_and_b32_e32 v225, 0xffff0000, v84
	v_fmamk_f32 v40, v40, 0x3fb504f3, v224
	v_fmamk_f32 v41, v41, 0x3fb504f3, v225
	v_lshlrev_b32_e32 v224, 16, v85
	v_and_b32_e32 v225, 0xffff0000, v85
	v_fmamk_f32 v42, v42, 0x3fb504f3, v224
	v_fmamk_f32 v43, v43, 0x3fb504f3, v225
	v_add_f32_e32 v226, v40, v41
	v_add_f32_e32 v227, v42, v43
	v_add_f32_e32 v226, v226, v227
	v_add_f32_e32 v168, v168, v226
	v_lshlrev_b32_e32 v224, 16, v86
	v_and_b32_e32 v225, 0xffff0000, v86
	v_fmamk_f32 v44, v44, 0x3fb504f3, v224
	v_fmamk_f32 v45, v45, 0x3fb504f3, v225
	v_lshlrev_b32_e32 v224, 16, v87
	v_and_b32_e32 v225, 0xffff0000, v87
	v_fmamk_f32 v46, v46, 0x3fb504f3, v224
	v_fmamk_f32 v47, v47, 0x3fb504f3, v225
	v_add_f32_e32 v226, v44, v45
	v_add_f32_e32 v227, v46, v47
	v_add_f32_e32 v226, v226, v227
	v_add_f32_e32 v168, v168, v226
	s_waitcnt vmcnt(0)
; template <int NR>
; DI void ln_rows(const Params& P, const LnSpec& sp, int row, int stride, int lane) {
;     ...
; #pragma unroll
;     for (int k = 0; k < NR; ++k) {
;         s[k] = 0.f;
; #pragma unroll
;         for (int i = 0; i < 4; ++i) s[k] += (v[k][i][0] + v[k][i][1]) + (v[k][i][2] + v[k][i][3]);
;     }
; #pragma unroll
;     for (int o = 32; o >= 1; o >>= 1)
; #pragma unroll
;         for (int k = 0; k < NR; ++k) s[k] += __shfl_xor(s[k], o);
; #pragma unroll
;     for (int k = 0; k < NR; ++k) {
;         s[k] *= (1.f / 1024.f); qv[k] = 0.f;
; #pragma unroll
;         for (int i = 0; i < 4; ++i)
; #pragma unroll
;             for (int j = 0; j < 4; ++j) { const float d = v[k][i][j] - s[k]; qv[k] += d * d; }
;     }
	v_lshlrev_b32_e32 v224, 16, v88
	v_and_b32_e32 v225, 0xffff0000, v88
	v_fmamk_f32 v48, v48, 0x3fb504f3, v224
	v_fmamk_f32 v49, v49, 0x3fb504f3, v225
	v_lshlrev_b32_e32 v224, 16, v89
	v_and_b32_e32 v225, 0xffff0000, v89
	v_fmamk_f32 v50, v50, 0x3fb504f3, v224
	v_fmamk_f32 v51, v51, 0x3fb504f3, v225
	v_add_f32_e32 v226, v48, v49
	v_add_f32_e32 v227, v50, v51
	v_add_f32_e32 v226, v226, v227
	v_mov_b32_e32 v169, v226
	v_lshlrev_b32_e32 v224, 16, v90
	v_and_b32_e32 v225, 0xffff0000, v90
	v_fmamk_f32 v52, v52, 0x3fb504f3, v224
	v_fmamk_f32 v53, v53, 0x3fb504f3, v225
	v_lshlrev_b32_e32 v224, 16, v91
	v_and_b32_e32 v225, 0xffff0000, v91
	v_fmamk_f32 v54, v54, 0x3fb504f3, v224
	v_fmamk_f32 v55, v55, 0x3fb504f3, v225
	v_add_f32_e32 v226, v52, v53
	v_add_f32_e32 v227, v54, v55
	v_add_f32_e32 v226, v226, v227
	v_add_f32_e32 v169, v169, v226
	v_lshlrev_b32_e32 v224, 16, v92
	v_and_b32_e32 v225, 0xffff0000, v92
	v_fmamk_f32 v56, v56, 0x3fb504f3, v224
	v_fmamk_f32 v57, v57, 0x3fb504f3, v225
	v_lshlrev_b32_e32 v224, 16, v93
	v_and_b32_e32 v225, 0xffff0000, v93
	v_fmamk_f32 v58, v58, 0x3fb504f3, v224
	v_fmamk_f32 v59, v59, 0x3fb504f3, v225
	v_add_f32_e32 v226, v56, v57
	v_add_f32_e32 v227, v58, v59
	v_add_f32_e32 v226, v226, v227
	v_add_f32_e32 v169, v169, v226
	v_lshlrev_b32_e32 v224, 16, v94
	v_and_b32_e32 v225, 0xffff0000, v94
	v_fmamk_f32 v60, v60, 0x3fb504f3, v224
	v_fmamk_f32 v61, v61, 0x3fb504f3, v225
	v_lshlrev_b32_e32 v224, 16, v95
	v_and_b32_e32 v225, 0xffff0000, v95
	v_fmamk_f32 v62, v62, 0x3fb504f3, v224
	v_fmamk_f32 v63, v63, 0x3fb504f3, v225
	v_add_f32_e32 v226, v60, v61
	v_add_f32_e32 v227, v62, v63
	v_add_f32_e32 v226, v226, v227
	v_add_f32_e32 v169, v169, v226
	ds_bpermute_b32 v178, v160, v166
	ds_bpermute_b32 v179, v160, v167
	ds_bpermute_b32 v180, v160, v168
	ds_bpermute_b32 v181, v160, v169
	s_waitcnt lgkmcnt(0)
	v_add_f32_e32 v166, v166, v178
	v_add_f32_e32 v167, v167, v179
	v_add_f32_e32 v168, v168, v180
	v_add_f32_e32 v169, v169, v181
	ds_bpermute_b32 v178, v161, v166
	ds_bpermute_b32 v179, v161, v167
	ds_bpermute_b32 v180, v161, v168
	ds_bpermute_b32 v181, v161, v169
	s_waitcnt lgkmcnt(0)
	v_add_f32_e32 v166, v166, v178
	v_add_f32_e32 v167, v167, v179
	v_add_f32_e32 v168, v168, v180
	v_add_f32_e32 v169, v169, v181
	ds_bpermute_b32 v178, v162, v166
	ds_bpermute_b32 v179, v162, v167
	ds_bpermute_b32 v180, v162, v168
	ds_bpermute_b32 v181, v162, v169
	s_waitcnt lgkmcnt(0)
	v_add_f32_e32 v166, v166, v178
	v_add_f32_e32 v167, v167, v179
	v_add_f32_e32 v168, v168, v180
	v_add_f32_e32 v169, v169, v181
	ds_bpermute_b32 v178, v163, v166
	ds_bpermute_b32 v179, v163, v167
	ds_bpermute_b32 v180, v163, v168
	ds_bpermute_b32 v181, v163, v169
	s_waitcnt lgkmcnt(0)
	v_add_f32_e32 v166, v166, v178
	v_add_f32_e32 v167, v167, v179
	v_add_f32_e32 v168, v168, v180
	v_add_f32_e32 v169, v169, v181
	ds_bpermute_b32 v178, v164, v166
	ds_bpermute_b32 v179, v164, v167
	ds_bpermute_b32 v180, v164, v168
	ds_bpermute_b32 v181, v164, v169
	s_waitcnt lgkmcnt(0)
	v_add_f32_e32 v166, v166, v178
	v_add_f32_e32 v167, v167, v179
	v_add_f32_e32 v168, v168, v180
	v_add_f32_e32 v169, v169, v181
	ds_bpermute_b32 v178, v165, v166
	ds_bpermute_b32 v179, v165, v167
	ds_bpermute_b32 v180, v165, v168
	ds_bpermute_b32 v181, v165, v169
	s_waitcnt lgkmcnt(0)
	v_add_f32_e32 v166, v166, v178
	v_add_f32_e32 v167, v167, v179
	v_add_f32_e32 v168, v168, v180
	v_add_f32_e32 v169, v169, v181
	v_mul_f32_e32 v166, 0x3a800000, v166
	v_mul_f32_e32 v167, 0x3a800000, v167
	v_mul_f32_e32 v168, 0x3a800000, v168
	v_mul_f32_e32 v169, 0x3a800000, v169
	v_mov_b32_e32 v174, 0
	v_sub_f32_e32 v0, v0, v166
	v_fmac_f32_e32 v174, v0, v0
	v_sub_f32_e32 v1, v1, v166
	v_fmac_f32_e32 v174, v1, v1
	v_sub_f32_e32 v2, v2, v166
	v_fmac_f32_e32 v174, v2, v2
	v_sub_f32_e32 v3, v3, v166
	v_fmac_f32_e32 v174, v3, v3
	v_sub_f32_e32 v4, v4, v166
	v_fmac_f32_e32 v174, v4, v4
	v_sub_f32_e32 v5, v5, v166
	v_fmac_f32_e32 v174, v5, v5
	v_sub_f32_e32 v6, v6, v166
	v_fmac_f32_e32 v174, v6, v6
	v_sub_f32_e32 v7, v7, v166
	v_fmac_f32_e32 v174, v7, v7
	v_sub_f32_e32 v8, v8, v166
	v_fmac_f32_e32 v174, v8, v8
	v_sub_f32_e32 v9, v9, v166
	v_fmac_f32_e32 v174, v9, v9
	v_sub_f32_e32 v10, v10, v166
	v_fmac_f32_e32 v174, v10, v10
	v_sub_f32_e32 v11, v11, v166
	v_fmac_f32_e32 v174, v11, v11
	v_sub_f32_e32 v12, v12, v166
	v_fmac_f32_e32 v174, v12, v12
	v_sub_f32_e32 v13, v13, v166
	v_fmac_f32_e32 v174, v13, v13
	v_sub_f32_e32 v14, v14, v166
	v_fmac_f32_e32 v174, v14, v14
	v_sub_f32_e32 v15, v15, v166
	v_fmac_f32_e32 v174, v15, v15
	v_mov_b32_e32 v175, 0
	v_sub_f32_e32 v16, v16, v167
	v_fmac_f32_e32 v175, v16, v16
	v_sub_f32_e32 v17, v17, v167
	v_fmac_f32_e32 v175, v17, v17
	v_sub_f32_e32 v18, v18, v167
	v_fmac_f32_e32 v175, v18, v18
	v_sub_f32_e32 v19, v19, v167
	v_fmac_f32_e32 v175, v19, v19
	v_sub_f32_e32 v20, v20, v167
	v_fmac_f32_e32 v175, v20, v20
	v_sub_f32_e32 v21, v21, v167
	v_fmac_f32_e32 v175, v21, v21
	v_sub_f32_e32 v22, v22, v167
	v_fmac_f32_e32 v175, v22, v22
	v_sub_f32_e32 v23, v23, v167
	v_fmac_f32_e32 v175, v23, v23
	v_sub_f32_e32 v24, v24, v167
	v_fmac_f32_e32 v175, v24, v24
	v_sub_f32_e32 v25, v25, v167
	v_fmac_f32_e32 v175, v25, v25
	v_sub_f32_e32 v26, v26, v167
	v_fmac_f32_e32 v175, v26, v26
	v_sub_f32_e32 v27, v27, v167
	v_fmac_f32_e32 v175, v27, v27
	v_sub_f32_e32 v28, v28, v167
	v_fmac_f32_e32 v175, v28, v28
	v_sub_f32_e32 v29, v29, v167
	v_fmac_f32_e32 v175, v29, v29
	v_sub_f32_e32 v30, v30, v167
	v_fmac_f32_e32 v175, v30, v30
	v_sub_f32_e32 v31, v31, v167
	v_fmac_f32_e32 v175, v31, v31
	v_mov_b32_e32 v176, 0
	v_sub_f32_e32 v32, v32, v168
	v_fmac_f32_e32 v176, v32, v32
	v_sub_f32_e32 v33, v33, v168
; DI unsigned pk2(float a, float b) { f32x2 v = {a, b}; bfx2 r = __builtin_convertvector(v, bfx2); return __builtin_bit_cast(unsigned, r); }
; template <int NR>
; DI void ln_rows(const Params& P, const LnSpec& sp, int row, int stride, int lane) {
;     ...
;     for (int k = 0; k < NR; ++k) {
;         s[k] *= (1.f / 1024.f); qv[k] = 0.f;
; #pragma unroll
;         for (int i = 0; i < 4; ++i)
; #pragma unroll
;             for (int j = 0; j < 4; ++j) { const float d = v[k][i][j] - s[k]; qv[k] += d * d; }
;     }
; #pragma unroll
;     for (int o = 32; o >= 1; o >>= 1)
; #pragma unroll
;         for (int k = 0; k < NR; ++k) qv[k] += __shfl_xor(qv[k], o);
; #pragma unroll
;     for (int k = 0; k < NR; ++k) {
;         const int r = row + k * stride;
;         const float mu = s[k], rstd = rsqrtf(qv[k] * (1.f / 1024.f) + 1e-6f);
;         const int sidx = r < RL ? (r >> 13) : 4;
;         const float* sh = MOD + (size_t)(sp.lnext * 5 + sidx) * 9216 + sp.mshift * 1024; const float* scl = sh + 1024;
;         float* xp = X + (size_t)r * 1024;
; #pragma unroll
;         for (int i = 0; i < 4; ++i) {
;             const int c = (i * 64 + lane) * 4;
;             const f32x4 gg = *(const f32x4*)(g + c), b4 = *(const f32x4*)(bb + c);
;             f32x4 y;
; #pragma unroll
;             for (int j = 0; j < 4; ++j) y[j] = (v[k][i][j] - mu) * rstd * gg[j] + b4[j];
;             if (sp.final_) { __builtin_nontemporal_store(y, (f32x4*)(P.out + (size_t)r * 1024 + c)); }
;             else {
;                 __builtin_nontemporal_store(y, (f32x4*)(xp + c));
;                 const f32x4 a = *(const f32x4*)(sh + c), sg = *(const f32x4*)(scl + c);
;                 u32x2 w; w.x = pk2(y[0] * (1.f + sg[0]) + a[0], y[1] * (1.f + sg[1]) + a[1]); w.y = pk2(y[2] * (1.f + sg[2]) + a[2], y[3] * (1.f + sg[3]) + a[3]);
;                 *(u32x2*)(XM + (size_t)r * 1024 + c) = w;
	v_fmac_f32_e32 v176, v33, v33
	v_sub_f32_e32 v34, v34, v168
	v_fmac_f32_e32 v176, v34, v34
	v_sub_f32_e32 v35, v35, v168
	v_fmac_f32_e32 v176, v35, v35
	v_sub_f32_e32 v36, v36, v168
	v_fmac_f32_e32 v176, v36, v36
	v_sub_f32_e32 v37, v37, v168
	v_fmac_f32_e32 v176, v37, v37
	v_sub_f32_e32 v38, v38, v168
	v_fmac_f32_e32 v176, v38, v38
	v_sub_f32_e32 v39, v39, v168
	v_fmac_f32_e32 v176, v39, v39
	v_sub_f32_e32 v40, v40, v168
	v_fmac_f32_e32 v176, v40, v40
	v_sub_f32_e32 v41, v41, v168
	v_fmac_f32_e32 v176, v41, v41
	v_sub_f32_e32 v42, v42, v168
	v_fmac_f32_e32 v176, v42, v42
	v_sub_f32_e32 v43, v43, v168
	v_fmac_f32_e32 v176, v43, v43
	v_sub_f32_e32 v44, v44, v168
	v_fmac_f32_e32 v176, v44, v44
	v_sub_f32_e32 v45, v45, v168
	v_fmac_f32_e32 v176, v45, v45
	v_sub_f32_e32 v46, v46, v168
	v_fmac_f32_e32 v176, v46, v46
	v_sub_f32_e32 v47, v47, v168
	v_fmac_f32_e32 v176, v47, v47
	v_mov_b32_e32 v177, 0
	v_sub_f32_e32 v48, v48, v169
	v_fmac_f32_e32 v177, v48, v48
	v_sub_f32_e32 v49, v49, v169
	v_fmac_f32_e32 v177, v49, v49
	v_sub_f32_e32 v50, v50, v169
	v_fmac_f32_e32 v177, v50, v50
	v_sub_f32_e32 v51, v51, v169
	v_fmac_f32_e32 v177, v51, v51
	v_sub_f32_e32 v52, v52, v169
	v_fmac_f32_e32 v177, v52, v52
	v_sub_f32_e32 v53, v53, v169
	v_fmac_f32_e32 v177, v53, v53
	v_sub_f32_e32 v54, v54, v169
	v_fmac_f32_e32 v177, v54, v54
	v_sub_f32_e32 v55, v55, v169
	v_fmac_f32_e32 v177, v55, v55
	v_sub_f32_e32 v56, v56, v169
	v_fmac_f32_e32 v177, v56, v56
	v_sub_f32_e32 v57, v57, v169
	v_fmac_f32_e32 v177, v57, v57
	v_sub_f32_e32 v58, v58, v169
	v_fmac_f32_e32 v177, v58, v58
	v_sub_f32_e32 v59, v59, v169
	v_fmac_f32_e32 v177, v59, v59
	v_sub_f32_e32 v60, v60, v169
	v_fmac_f32_e32 v177, v60, v60
	v_sub_f32_e32 v61, v61, v169
	v_fmac_f32_e32 v177, v61, v61
	v_sub_f32_e32 v62, v62, v169
	v_fmac_f32_e32 v177, v62, v62
	v_sub_f32_e32 v63, v63, v169
	v_fmac_f32_e32 v177, v63, v63
	ds_bpermute_b32 v178, v160, v174
	ds_bpermute_b32 v179, v160, v175
	ds_bpermute_b32 v180, v160, v176
	ds_bpermute_b32 v181, v160, v177
	s_waitcnt lgkmcnt(0)
	v_add_f32_e32 v174, v174, v178
	v_add_f32_e32 v175, v175, v179
	v_add_f32_e32 v176, v176, v180
	v_add_f32_e32 v177, v177, v181
	ds_bpermute_b32 v178, v161, v174
	ds_bpermute_b32 v179, v161, v175
	ds_bpermute_b32 v180, v161, v176
	ds_bpermute_b32 v181, v161, v177
	s_waitcnt lgkmcnt(0)
	v_add_f32_e32 v174, v174, v178
	v_add_f32_e32 v175, v175, v179
	v_add_f32_e32 v176, v176, v180
	v_add_f32_e32 v177, v177, v181
	ds_bpermute_b32 v178, v162, v174
	ds_bpermute_b32 v179, v162, v175
	ds_bpermute_b32 v180, v162, v176
	ds_bpermute_b32 v181, v162, v177
	s_waitcnt lgkmcnt(0)
	v_add_f32_e32 v174, v174, v178
	v_add_f32_e32 v175, v175, v179
	v_add_f32_e32 v176, v176, v180
	v_add_f32_e32 v177, v177, v181
	ds_bpermute_b32 v178, v163, v174
	ds_bpermute_b32 v179, v163, v175
	ds_bpermute_b32 v180, v163, v176
	ds_bpermute_b32 v181, v163, v177
	s_waitcnt lgkmcnt(0)
	v_add_f32_e32 v174, v174, v178
	v_add_f32_e32 v175, v175, v179
	v_add_f32_e32 v176, v176, v180
	v_add_f32_e32 v177, v177, v181
	ds_bpermute_b32 v178, v164, v174
	ds_bpermute_b32 v179, v164, v175
	ds_bpermute_b32 v180, v164, v176
	ds_bpermute_b32 v181, v164, v177
	s_waitcnt lgkmcnt(0)
	v_add_f32_e32 v174, v174, v178
	v_add_f32_e32 v175, v175, v179
	v_add_f32_e32 v176, v176, v180
	v_add_f32_e32 v177, v177, v181
	ds_bpermute_b32 v178, v165, v174
	ds_bpermute_b32 v179, v165, v175
	ds_bpermute_b32 v180, v165, v176
	ds_bpermute_b32 v181, v165, v177
	s_waitcnt lgkmcnt(0)
	v_add_f32_e32 v174, v174, v178
	v_add_f32_e32 v175, v175, v179
	v_add_f32_e32 v176, v176, v180
	v_add_f32_e32 v177, v177, v181
	v_fmaak_f32 v174, v228, v174, 0x358637bd
	v_fmaak_f32 v175, v228, v175, 0x358637bd
	v_fmaak_f32 v176, v228, v176, 0x358637bd
	v_fmaak_f32 v177, v228, v177, 0x358637bd
	v_rsq_f32_e32 v182, v174
	v_rsq_f32_e32 v183, v175
	v_rsq_f32_e32 v184, v176
	v_rsq_f32_e32 v185, v177
	s_waitcnt vmcnt(0)
	s_cmp_eq_u32 s18, 1
	s_cbranch_scc1 .Lmy_ln1_final
	v_add_f32_e32 v144, 1.0, v144
	v_add_f32_e32 v145, 1.0, v145
	v_add_f32_e32 v146, 1.0, v146
	v_add_f32_e32 v147, 1.0, v147
	v_add_f32_e32 v148, 1.0, v148
	v_add_f32_e32 v149, 1.0, v149
	v_add_f32_e32 v150, 1.0, v150
	v_add_f32_e32 v151, 1.0, v151
	v_add_f32_e32 v152, 1.0, v152
	v_add_f32_e32 v153, 1.0, v153
	v_add_f32_e32 v154, 1.0, v154
	v_add_f32_e32 v155, 1.0, v155
	v_add_f32_e32 v156, 1.0, v156
	v_add_f32_e32 v157, 1.0, v157
	v_add_f32_e32 v158, 1.0, v158
	v_add_f32_e32 v159, 1.0, v159
	v_mul_f32_e32 v0, v0, v182
	v_mul_f32_e32 v1, v1, v182
	v_mul_f32_e32 v2, v2, v182
	v_mul_f32_e32 v3, v3, v182
	v_fma_f32 v0, v0, v96, v112
	v_fma_f32 v1, v1, v97, v113
	v_fma_f32 v2, v2, v98, v114
	v_fma_f32 v3, v3, v99, v115
	global_store_dwordx4 v218, v[0:3], s[94:95] nt sc1
	v_fma_f32 v224, v0, v144, v128
	v_fma_f32 v225, v1, v145, v129
	v_fma_f32 v226, v2, v146, v130
	v_fma_f32 v227, v3, v147, v131
	v_cvt_pk_bf16_f32 v232, v224, v225
	v_cvt_pk_bf16_f32 v233, v226, v227
	global_store_dwordx2 v222, v[232:233], s[94:95] sc1
	v_mul_f32_e32 v4, v4, v182
	v_mul_f32_e32 v5, v5, v182
	v_mul_f32_e32 v6, v6, v182
	v_mul_f32_e32 v7, v7, v182
	v_fma_f32 v4, v4, v100, v116
	v_fma_f32 v5, v5, v101, v117
	v_fma_f32 v6, v6, v102, v118
	v_fma_f32 v7, v7, v103, v119
	global_store_dwordx4 v218, v[4:7], s[94:95] offset:1024 nt sc1
	v_fma_f32 v224, v4, v148, v132
	v_fma_f32 v225, v5, v149, v133
	v_fma_f32 v226, v6, v150, v134
	v_fma_f32 v227, v7, v151, v135
	v_cvt_pk_bf16_f32 v232, v224, v225
	v_cvt_pk_bf16_f32 v233, v226, v227
	global_store_dwordx2 v222, v[232:233], s[94:95] offset:512 sc1
	v_mul_f32_e32 v8, v8, v182
	v_mul_f32_e32 v9, v9, v182
	v_mul_f32_e32 v10, v10, v182
	v_mul_f32_e32 v11, v11, v182
; DI unsigned pk2(float a, float b) { f32x2 v = {a, b}; bfx2 r = __builtin_convertvector(v, bfx2); return __builtin_bit_cast(unsigned, r); }
; template <int NR>
; DI void ln_rows(const Params& P, const LnSpec& sp, int row, int stride, int lane) {
;     ...
;         for (int i = 0; i < 4; ++i) {
;             const int c = (i * 64 + lane) * 4;
;             const f32x4 gg = *(const f32x4*)(g + c), b4 = *(const f32x4*)(bb + c);
;             f32x4 y;
; #pragma unroll
;             for (int j = 0; j < 4; ++j) y[j] = (v[k][i][j] - mu) * rstd * gg[j] + b4[j];
;             if (sp.final_) { __builtin_nontemporal_store(y, (f32x4*)(P.out + (size_t)r * 1024 + c)); }
;             else {
;                 __builtin_nontemporal_store(y, (f32x4*)(xp + c));
;                 const f32x4 a = *(const f32x4*)(sh + c), sg = *(const f32x4*)(scl + c);
;                 u32x2 w; w.x = pk2(y[0] * (1.f + sg[0]) + a[0], y[1] * (1.f + sg[1]) + a[1]); w.y = pk2(y[2] * (1.f + sg[2]) + a[2], y[3] * (1.f + sg[3]) + a[3]);
;                 *(u32x2*)(XM + (size_t)r * 1024 + c) = w;
	v_fma_f32 v8, v8, v104, v120
	v_fma_f32 v9, v9, v105, v121
	v_fma_f32 v10, v10, v106, v122
	v_fma_f32 v11, v11, v107, v123
	global_store_dwordx4 v218, v[8:11], s[94:95] offset:2048 nt sc1
	v_fma_f32 v224, v8, v152, v136
	v_fma_f32 v225, v9, v153, v137
	v_fma_f32 v226, v10, v154, v138
	v_fma_f32 v227, v11, v155, v139
	v_cvt_pk_bf16_f32 v232, v224, v225
	v_cvt_pk_bf16_f32 v233, v226, v227
	global_store_dwordx2 v222, v[232:233], s[94:95] offset:1024 sc1
	v_mul_f32_e32 v12, v12, v182
	v_mul_f32_e32 v13, v13, v182
	v_mul_f32_e32 v14, v14, v182
	v_mul_f32_e32 v15, v15, v182
	v_fma_f32 v12, v12, v108, v124
	v_fma_f32 v13, v13, v109, v125
	v_fma_f32 v14, v14, v110, v126
	v_fma_f32 v15, v15, v111, v127
	global_store_dwordx4 v218, v[12:15], s[94:95] offset:3072 nt sc1
	v_fma_f32 v224, v12, v156, v140
	v_fma_f32 v225, v13, v157, v141
	v_fma_f32 v226, v14, v158, v142
	v_fma_f32 v227, v15, v159, v143
	v_cvt_pk_bf16_f32 v232, v224, v225
	v_cvt_pk_bf16_f32 v233, v226, v227
	global_store_dwordx2 v222, v[232:233], s[94:95] offset:1536 sc1
	v_mul_f32_e32 v16, v16, v183
	v_mul_f32_e32 v17, v17, v183
	v_mul_f32_e32 v18, v18, v183
	v_mul_f32_e32 v19, v19, v183
	v_fma_f32 v16, v16, v96, v112
	v_fma_f32 v17, v17, v97, v113
	v_fma_f32 v18, v18, v98, v114
	v_fma_f32 v19, v19, v99, v115
	global_store_dwordx4 v219, v[16:19], s[94:95] nt sc1
	v_fma_f32 v224, v16, v144, v128
	v_fma_f32 v225, v17, v145, v129
	v_fma_f32 v226, v18, v146, v130
	v_fma_f32 v227, v19, v147, v131
	v_cvt_pk_bf16_f32 v232, v224, v225
	v_cvt_pk_bf16_f32 v233, v226, v227
	global_store_dwordx2 v222, v[232:233], s[94:95] offset:2048 sc1
	v_mul_f32_e32 v20, v20, v183
	v_mul_f32_e32 v21, v21, v183
	v_mul_f32_e32 v22, v22, v183
	v_mul_f32_e32 v23, v23, v183
	v_fma_f32 v20, v20, v100, v116
	v_fma_f32 v21, v21, v101, v117
	v_fma_f32 v22, v22, v102, v118
	v_fma_f32 v23, v23, v103, v119
	global_store_dwordx4 v219, v[20:23], s[94:95] offset:1024 nt sc1
	v_fma_f32 v224, v20, v148, v132
	v_fma_f32 v225, v21, v149, v133
	v_fma_f32 v226, v22, v150, v134
	v_fma_f32 v227, v23, v151, v135
	v_cvt_pk_bf16_f32 v232, v224, v225
	v_cvt_pk_bf16_f32 v233, v226, v227
	global_store_dwordx2 v222, v[232:233], s[94:95] offset:2560 sc1
	v_mul_f32_e32 v24, v24, v183
	v_mul_f32_e32 v25, v25, v183
	v_mul_f32_e32 v26, v26, v183
	v_mul_f32_e32 v27, v27, v183
	v_fma_f32 v24, v24, v104, v120
	v_fma_f32 v25, v25, v105, v121
	v_fma_f32 v26, v26, v106, v122
	v_fma_f32 v27, v27, v107, v123
	global_store_dwordx4 v219, v[24:27], s[94:95] offset:2048 nt sc1
	v_fma_f32 v224, v24, v152, v136
	v_fma_f32 v225, v25, v153, v137
	v_fma_f32 v226, v26, v154, v138
	v_fma_f32 v227, v27, v155, v139
	v_cvt_pk_bf16_f32 v232, v224, v225
	v_cvt_pk_bf16_f32 v233, v226, v227
	global_store_dwordx2 v222, v[232:233], s[94:95] offset:3072 sc1
	v_mul_f32_e32 v28, v28, v183
	v_mul_f32_e32 v29, v29, v183
	v_mul_f32_e32 v30, v30, v183
	v_mul_f32_e32 v31, v31, v183
	v_fma_f32 v28, v28, v108, v124
	v_fma_f32 v29, v29, v109, v125
	v_fma_f32 v30, v30, v110, v126
	v_fma_f32 v31, v31, v111, v127
	global_store_dwordx4 v219, v[28:31], s[94:95] offset:3072 nt sc1
	v_fma_f32 v224, v28, v156, v140
	v_fma_f32 v225, v29, v157, v141
	v_fma_f32 v226, v30, v158, v142
	v_fma_f32 v227, v31, v159, v143
	v_cvt_pk_bf16_f32 v232, v224, v225
	v_cvt_pk_bf16_f32 v233, v226, v227
	global_store_dwordx2 v222, v[232:233], s[94:95] offset:3584 sc1
	v_mul_f32_e32 v32, v32, v184
	v_mul_f32_e32 v33, v33, v184
	v_mul_f32_e32 v34, v34, v184
	v_mul_f32_e32 v35, v35, v184
	v_fma_f32 v32, v32, v96, v112
	v_fma_f32 v33, v33, v97, v113
	v_fma_f32 v34, v34, v98, v114
	v_fma_f32 v35, v35, v99, v115
	global_store_dwordx4 v220, v[32:35], s[94:95] nt sc1
	v_fma_f32 v224, v32, v144, v128
	v_fma_f32 v225, v33, v145, v129
	v_fma_f32 v226, v34, v146, v130
	v_fma_f32 v227, v35, v147, v131
	v_cvt_pk_bf16_f32 v232, v224, v225
	v_cvt_pk_bf16_f32 v233, v226, v227
	global_store_dwordx2 v223, v[232:233], s[94:95] sc1
	v_mul_f32_e32 v36, v36, v184
	v_mul_f32_e32 v37, v37, v184
	v_mul_f32_e32 v38, v38, v184
	v_mul_f32_e32 v39, v39, v184
	v_fma_f32 v36, v36, v100, v116
	v_fma_f32 v37, v37, v101, v117
	v_fma_f32 v38, v38, v102, v118
	v_fma_f32 v39, v39, v103, v119
	global_store_dwordx4 v220, v[36:39], s[94:95] offset:1024 nt sc1
	v_fma_f32 v224, v36, v148, v132
	v_fma_f32 v225, v37, v149, v133
	v_fma_f32 v226, v38, v150, v134
	v_fma_f32 v227, v39, v151, v135
	v_cvt_pk_bf16_f32 v232, v224, v225
	v_cvt_pk_bf16_f32 v233, v226, v227
	global_store_dwordx2 v223, v[232:233], s[94:95] offset:512 sc1
	v_mul_f32_e32 v40, v40, v184
	v_mul_f32_e32 v41, v41, v184
	v_mul_f32_e32 v42, v42, v184
	v_mul_f32_e32 v43, v43, v184
	v_fma_f32 v40, v40, v104, v120
	v_fma_f32 v41, v41, v105, v121
	v_fma_f32 v42, v42, v106, v122
	v_fma_f32 v43, v43, v107, v123
	global_store_dwordx4 v220, v[40:43], s[94:95] offset:2048 nt sc1
	v_fma_f32 v224, v40, v152, v136
	v_fma_f32 v225, v41, v153, v137
	v_fma_f32 v226, v42, v154, v138
	v_fma_f32 v227, v43, v155, v139
	v_cvt_pk_bf16_f32 v232, v224, v225
	v_cvt_pk_bf16_f32 v233, v226, v227
	global_store_dwordx2 v223, v[232:233], s[94:95] offset:1024 sc1
	v_mul_f32_e32 v44, v44, v184
	v_mul_f32_e32 v45, v45, v184
	v_mul_f32_e32 v46, v46, v184
	v_mul_f32_e32 v47, v47, v184
	v_fma_f32 v44, v44, v108, v124
	v_fma_f32 v45, v45, v109, v125
	v_fma_f32 v46, v46, v110, v126
	v_fma_f32 v47, v47, v111, v127
	global_store_dwordx4 v220, v[44:47], s[94:95] offset:3072 nt sc1
	v_fma_f32 v224, v44, v156, v140
	v_fma_f32 v225, v45, v157, v141
	v_fma_f32 v226, v46, v158, v142
	v_fma_f32 v227, v47, v159, v143
	v_cvt_pk_bf16_f32 v232, v224, v225
	v_cvt_pk_bf16_f32 v233, v226, v227
	global_store_dwordx2 v223, v[232:233], s[94:95] offset:1536 sc1
; DI unsigned pk2(float a, float b) { f32x2 v = {a, b}; bfx2 r = __builtin_convertvector(v, bfx2); return __builtin_bit_cast(unsigned, r); }
; template <int NR>
; DI void ln_rows(const Params& P, const LnSpec& sp, int row, int stride, int lane) {
;     ...
;         for (int i = 0; i < 4; ++i) {
;             const int c = (i * 64 + lane) * 4;
;             const f32x4 gg = *(const f32x4*)(g + c), b4 = *(const f32x4*)(bb + c);
;             f32x4 y;
; #pragma unroll
;             for (int j = 0; j < 4; ++j) y[j] = (v[k][i][j] - mu) * rstd * gg[j] + b4[j];
;             if (sp.final_) { __builtin_nontemporal_store(y, (f32x4*)(P.out + (size_t)r * 1024 + c)); }
;             else {
;                 __builtin_nontemporal_store(y, (f32x4*)(xp + c));
;                 const f32x4 a = *(const f32x4*)(sh + c), sg = *(const f32x4*)(scl + c);
;                 u32x2 w; w.x = pk2(y[0] * (1.f + sg[0]) + a[0], y[1] * (1.f + sg[1]) + a[1]); w.y = pk2(y[2] * (1.f + sg[2]) + a[2], y[3] * (1.f + sg[3]) + a[3]);
;                 *(u32x2*)(XM + (size_t)r * 1024 + c) = w;
	v_mul_f32_e32 v48, v48, v185
	v_mul_f32_e32 v49, v49, v185
	v_mul_f32_e32 v50, v50, v185
	v_mul_f32_e32 v51, v51, v185
	v_fma_f32 v48, v48, v96, v112
	v_fma_f32 v49, v49, v97, v113
	v_fma_f32 v50, v50, v98, v114
	v_fma_f32 v51, v51, v99, v115
	global_store_dwordx4 v221, v[48:51], s[94:95] nt sc1
	v_fma_f32 v224, v48, v144, v128
	v_fma_f32 v225, v49, v145, v129
	v_fma_f32 v226, v50, v146, v130
	v_fma_f32 v227, v51, v147, v131
	v_cvt_pk_bf16_f32 v232, v224, v225
	v_cvt_pk_bf16_f32 v233, v226, v227
	global_store_dwordx2 v223, v[232:233], s[94:95] offset:2048 sc1
	v_mul_f32_e32 v52, v52, v185
	v_mul_f32_e32 v53, v53, v185
	v_mul_f32_e32 v54, v54, v185
	v_mul_f32_e32 v55, v55, v185
	v_fma_f32 v52, v52, v100, v116
	v_fma_f32 v53, v53, v101, v117
	v_fma_f32 v54, v54, v102, v118
	v_fma_f32 v55, v55, v103, v119
	global_store_dwordx4 v221, v[52:55], s[94:95] offset:1024 nt sc1
	v_fma_f32 v224, v52, v148, v132
	v_fma_f32 v225, v53, v149, v133
	v_fma_f32 v226, v54, v150, v134
	v_fma_f32 v227, v55, v151, v135
	v_cvt_pk_bf16_f32 v232, v224, v225
	v_cvt_pk_bf16_f32 v233, v226, v227
	global_store_dwordx2 v223, v[232:233], s[94:95] offset:2560 sc1
	v_mul_f32_e32 v56, v56, v185
	v_mul_f32_e32 v57, v57, v185
	v_mul_f32_e32 v58, v58, v185
	v_mul_f32_e32 v59, v59, v185
	v_fma_f32 v56, v56, v104, v120
	v_fma_f32 v57, v57, v105, v121
	v_fma_f32 v58, v58, v106, v122
	v_fma_f32 v59, v59, v107, v123
	global_store_dwordx4 v221, v[56:59], s[94:95] offset:2048 nt sc1
	v_fma_f32 v224, v56, v152, v136
	v_fma_f32 v225, v57, v153, v137
	v_fma_f32 v226, v58, v154, v138
	v_fma_f32 v227, v59, v155, v139
	v_cvt_pk_bf16_f32 v232, v224, v225
	v_cvt_pk_bf16_f32 v233, v226, v227
	global_store_dwordx2 v223, v[232:233], s[94:95] offset:3072 sc1
	v_mul_f32_e32 v60, v60, v185
	v_mul_f32_e32 v61, v61, v185
	v_mul_f32_e32 v62, v62, v185
	v_mul_f32_e32 v63, v63, v185
	v_fma_f32 v60, v60, v108, v124
	v_fma_f32 v61, v61, v109, v125
	v_fma_f32 v62, v62, v110, v126
	v_fma_f32 v63, v63, v111, v127
	global_store_dwordx4 v221, v[60:63], s[94:95] offset:3072 nt sc1
	v_fma_f32 v224, v60, v156, v140
	v_fma_f32 v225, v61, v157, v141
	v_fma_f32 v226, v62, v158, v142
	v_fma_f32 v227, v63, v159, v143
	v_cvt_pk_bf16_f32 v232, v224, v225
	v_cvt_pk_bf16_f32 v233, v226, v227
	global_store_dwordx2 v223, v[232:233], s[94:95] offset:3584 sc1
	s_branch .Lmy_ln1_next
; template <int NR>
; DI void ln_rows(const Params& P, const LnSpec& sp, int row, int stride, int lane) {
;     ...
;         for (int i = 0; i < 4; ++i) {
;             const int c = (i * 64 + lane) * 4;
;             const f32x4 gg = *(const f32x4*)(g + c), b4 = *(const f32x4*)(bb + c);
;             f32x4 y;
; #pragma unroll
;             for (int j = 0; j < 4; ++j) y[j] = (v[k][i][j] - mu) * rstd * gg[j] + b4[j];
;             if (sp.final_) { __builtin_nontemporal_store(y, (f32x4*)(P.out + (size_t)r * 1024 + c)); }
.Lmy_ln1_final:
	v_mul_f32_e32 v0, v0, v182
	v_mul_f32_e32 v1, v1, v182
	v_mul_f32_e32 v2, v2, v182
	v_mul_f32_e32 v3, v3, v182
	v_fma_f32 v0, v0, v96, v112
	v_fma_f32 v1, v1, v97, v113
	v_fma_f32 v2, v2, v98, v114
	v_fma_f32 v3, v3, v99, v115
	global_store_dwordx4 v218, v[0:3], s[92:93] nt sc1
	v_mul_f32_e32 v4, v4, v182
	v_mul_f32_e32 v5, v5, v182
	v_mul_f32_e32 v6, v6, v182
	v_mul_f32_e32 v7, v7, v182
	v_fma_f32 v4, v4, v100, v116
	v_fma_f32 v5, v5, v101, v117
	v_fma_f32 v6, v6, v102, v118
	v_fma_f32 v7, v7, v103, v119
	global_store_dwordx4 v218, v[4:7], s[92:93] offset:1024 nt sc1
	v_mul_f32_e32 v8, v8, v182
	v_mul_f32_e32 v9, v9, v182
	v_mul_f32_e32 v10, v10, v182
	v_mul_f32_e32 v11, v11, v182
	v_fma_f32 v8, v8, v104, v120
	v_fma_f32 v9, v9, v105, v121
	v_fma_f32 v10, v10, v106, v122
	v_fma_f32 v11, v11, v107, v123
	global_store_dwordx4 v218, v[8:11], s[92:93] offset:2048 nt sc1
	v_mul_f32_e32 v12, v12, v182
	v_mul_f32_e32 v13, v13, v182
	v_mul_f32_e32 v14, v14, v182
	v_mul_f32_e32 v15, v15, v182
	v_fma_f32 v12, v12, v108, v124
	v_fma_f32 v13, v13, v109, v125
	v_fma_f32 v14, v14, v110, v126
	v_fma_f32 v15, v15, v111, v127
	global_store_dwordx4 v218, v[12:15], s[92:93] offset:3072 nt sc1
	v_mul_f32_e32 v16, v16, v183
	v_mul_f32_e32 v17, v17, v183
	v_mul_f32_e32 v18, v18, v183
	v_mul_f32_e32 v19, v19, v183
	v_fma_f32 v16, v16, v96, v112
	v_fma_f32 v17, v17, v97, v113
	v_fma_f32 v18, v18, v98, v114
	v_fma_f32 v19, v19, v99, v115
	global_store_dwordx4 v219, v[16:19], s[92:93] nt sc1
	v_mul_f32_e32 v20, v20, v183
	v_mul_f32_e32 v21, v21, v183
	v_mul_f32_e32 v22, v22, v183
	v_mul_f32_e32 v23, v23, v183
	v_fma_f32 v20, v20, v100, v116
	v_fma_f32 v21, v21, v101, v117
	v_fma_f32 v22, v22, v102, v118
	v_fma_f32 v23, v23, v103, v119
	global_store_dwordx4 v219, v[20:23], s[92:93] offset:1024 nt sc1
	v_mul_f32_e32 v24, v24, v183
	v_mul_f32_e32 v25, v25, v183
	v_mul_f32_e32 v26, v26, v183
	v_mul_f32_e32 v27, v27, v183
	v_fma_f32 v24, v24, v104, v120
	v_fma_f32 v25, v25, v105, v121
	v_fma_f32 v26, v26, v106, v122
	v_fma_f32 v27, v27, v107, v123
	global_store_dwordx4 v219, v[24:27], s[92:93] offset:2048 nt sc1
	v_mul_f32_e32 v28, v28, v183
	v_mul_f32_e32 v29, v29, v183
	v_mul_f32_e32 v30, v30, v183
	v_mul_f32_e32 v31, v31, v183
	v_fma_f32 v28, v28, v108, v124
	v_fma_f32 v29, v29, v109, v125
	v_fma_f32 v30, v30, v110, v126
	v_fma_f32 v31, v31, v111, v127
	global_store_dwordx4 v219, v[28:31], s[92:93] offset:3072 nt sc1
	v_mul_f32_e32 v32, v32, v184
	v_mul_f32_e32 v33, v33, v184
	v_mul_f32_e32 v34, v34, v184
	v_mul_f32_e32 v35, v35, v184
	v_fma_f32 v32, v32, v96, v112
	v_fma_f32 v33, v33, v97, v113
	v_fma_f32 v34, v34, v98, v114
	v_fma_f32 v35, v35, v99, v115
	global_store_dwordx4 v220, v[32:35], s[92:93] nt sc1
	v_mul_f32_e32 v36, v36, v184
	v_mul_f32_e32 v37, v37, v184
	v_mul_f32_e32 v38, v38, v184
	v_mul_f32_e32 v39, v39, v184
	v_fma_f32 v36, v36, v100, v116
	v_fma_f32 v37, v37, v101, v117
	v_fma_f32 v38, v38, v102, v118
	v_fma_f32 v39, v39, v103, v119
	global_store_dwordx4 v220, v[36:39], s[92:93] offset:1024 nt sc1
	v_mul_f32_e32 v40, v40, v184
	v_mul_f32_e32 v41, v41, v184
	v_mul_f32_e32 v42, v42, v184
	v_mul_f32_e32 v43, v43, v184
	v_fma_f32 v40, v40, v104, v120
	v_fma_f32 v41, v41, v105, v121
	v_fma_f32 v42, v42, v106, v122
	v_fma_f32 v43, v43, v107, v123
	global_store_dwordx4 v220, v[40:43], s[92:93] offset:2048 nt sc1
	v_mul_f32_e32 v44, v44, v184
	v_mul_f32_e32 v45, v45, v184
	v_mul_f32_e32 v46, v46, v184
	v_mul_f32_e32 v47, v47, v184
	v_fma_f32 v44, v44, v108, v124
	v_fma_f32 v45, v45, v109, v125
	v_fma_f32 v46, v46, v110, v126
	v_fma_f32 v47, v47, v111, v127
	global_store_dwordx4 v220, v[44:47], s[92:93] offset:3072 nt sc1
	v_mul_f32_e32 v48, v48, v185
	v_mul_f32_e32 v49, v49, v185
	v_mul_f32_e32 v50, v50, v185
	v_mul_f32_e32 v51, v51, v185
	v_fma_f32 v48, v48, v96, v112
	v_fma_f32 v49, v49, v97, v113
	v_fma_f32 v50, v50, v98, v114
	v_fma_f32 v51, v51, v99, v115
	global_store_dwordx4 v221, v[48:51], s[92:93] nt sc1
	v_mul_f32_e32 v52, v52, v185
	v_mul_f32_e32 v53, v53, v185
	v_mul_f32_e32 v54, v54, v185
	v_mul_f32_e32 v55, v55, v185
	v_fma_f32 v52, v52, v100, v116
	v_fma_f32 v53, v53, v101, v117
	v_fma_f32 v54, v54, v102, v118
	v_fma_f32 v55, v55, v103, v119
	global_store_dwordx4 v221, v[52:55], s[92:93] offset:1024 nt sc1
	v_mul_f32_e32 v56, v56, v185
	v_mul_f32_e32 v57, v57, v185
	v_mul_f32_e32 v58, v58, v185
	v_mul_f32_e32 v59, v59, v185
	v_fma_f32 v56, v56, v104, v120
	v_fma_f32 v57, v57, v105, v121
	v_fma_f32 v58, v58, v106, v122
	v_fma_f32 v59, v59, v107, v123
	global_store_dwordx4 v221, v[56:59], s[92:93] offset:2048 nt sc1
	v_mul_f32_e32 v60, v60, v185
	v_mul_f32_e32 v61, v61, v185
	v_mul_f32_e32 v62, v62, v185
	v_mul_f32_e32 v63, v63, v185
	v_fma_f32 v60, v60, v108, v124
	v_fma_f32 v61, v61, v109, v125
	v_fma_f32 v62, v62, v110, v126
	v_fma_f32 v63, v63, v111, v127
	global_store_dwordx4 v221, v[60:63], s[92:93] offset:3072 nt sc1

; DI unsigned pk2(float a, float b) { f32x2 v = {a, b}; bfx2 r = __builtin_convertvector(v, bfx2); return __builtin_bit_cast(unsigned, r); }
; DI float bflo(unsigned u) { return __uint_as_float(u << 16); }
; DI float bfhi(unsigned u) { return __uint_as_float(u & 0xffff0000u); }
; DI void phase_od_pool(const Params& P) {
;     ...
;         const float ic = 1.f / (float)(hi - lo);
;         const u32x4 s = *(const u32x4*)(U + (size_t)row * 512 + c);
;         u32x4 o;
;         o.x = pk2(acc[0] * ic - bflo(s.x), acc[1] * ic - bfhi(s.x)); o.y = pk2(acc[2] * ic - bflo(s.y), acc[3] * ic - bfhi(s.y));
;         o.z = pk2(acc[4] * ic - bflo(s.z), acc[5] * ic - bfhi(s.z)); o.w = pk2(acc[6] * ic - bflo(s.w), acc[7] * ic - bfhi(s.w));
;         *(u32x4*)(PL + (size_t)row * 512 + c) = o;
.Lmy_pool_a15:
	s_mov_b64 exec, -1
	v_fma_f32 v64, v64, v84, -v72
	v_fma_f32 v65, v65, v84, -v73
	v_fma_f32 v66, v66, v84, -v74
	v_fma_f32 v67, v67, v84, -v75
	v_fma_f32 v68, v68, v84, -v76
	v_fma_f32 v69, v69, v84, -v77
	v_fma_f32 v70, v70, v84, -v78
	v_fma_f32 v71, v71, v84, -v79
	v_cvt_pk_bf16_f32 v92, v64, v65
	v_cvt_pk_bf16_f32 v93, v66, v67
	v_cvt_pk_bf16_f32 v94, v68, v69
	v_cvt_pk_bf16_f32 v95, v70, v71
	global_store_dwordx4 v91, v[92:95], s[94:95] sc1
	s_add_u32 s8, s8, s9
	s_cmp_lt_u32 s8, 0x8400
	s_cbranch_scc1 .Lmy_pool_loop
